# G1/G4 main loops: steady-state fast path (no tail conditions, constant vmcnt), segments open with resident-operand MFMAs, scalar/LDS/DMA work between MFMAs; old body kept for the last two iterations
# speedup vs baseline: 1.0031x; 1.0031x over previous
.Lgf_G4x_top:
	s_waitcnt vmcnt(4)
	s_waitcnt lgkmcnt(0)
	s_barrier
	v_mfma_f32_16x16x32_bf16 v[158:161], v[122:125], v[150:153], v[158:161]
	v_mfma_f32_16x16x32_bf16 v[94:97], v[126:129], v[150:153], v[94:97]
	s_add_i32 s28, s31, 0xfffe8000
	s_and_b32 s34, s28, 0x10000
	v_add_u32_e32 v170, s34, v230
	ds_read_b128 v[162:165], v170
	v_mfma_f32_16x16x32_bf16 v[62:65], v[130:133], v[150:153], v[62:65]
	ds_read_b128 v[166:169], v170 offset:1024
	v_mfma_f32_16x16x32_bf16 v[30:33], v[134:137], v[150:153], v[30:33]
	ds_read_b128 v[232:235], v170 offset:2048
	v_mfma_f32_16x16x32_bf16 v[118:121], v[122:125], v[146:149], v[118:121]
	ds_read_b128 v[236:239], v170 offset:3072
	s_and_b32 s89, s31, 0x18000
	s_add_i32 s89, s89, s88
	s_mov_b32 m0, s89
	v_mfma_f32_16x16x32_bf16 v[86:89], v[126:129], v[146:149], v[86:89]
	v_mfma_f32_16x16x32_bf16 v[54:57], v[130:133], v[146:149], v[54:57]
	global_load_lds_dwordx4 v186, s[90:91]
	s_add_i32 m0, s89, 0x2000
	v_mfma_f32_16x16x32_bf16 v[22:25], v[134:137], v[146:149], v[22:25]
	v_mfma_f32_16x16x32_bf16 v[110:113], v[122:125], v[142:145], v[110:113]
	v_mfma_f32_16x16x32_bf16 v[78:81], v[126:129], v[142:145], v[78:81]
	global_load_lds_dwordx4 v188, s[90:91]
	s_add_i32 m0, s89, 0x4000
	v_mfma_f32_16x16x32_bf16 v[46:49], v[130:133], v[142:145], v[46:49]
	v_mfma_f32_16x16x32_bf16 v[14:17], v[134:137], v[142:145], v[14:17]
	global_load_lds_dwordx4 v190, s[92:93]
	s_add_i32 m0, s89, 0x6000
	v_mfma_f32_16x16x32_bf16 v[102:105], v[122:125], v[138:141], v[102:105]
	v_mfma_f32_16x16x32_bf16 v[70:73], v[126:129], v[138:141], v[70:73]
	global_load_lds_dwordx4 v192, s[92:93]
	s_add_u32 s90, s90, 64
	s_addc_u32 s91, s91, 0
	s_add_u32 s92, s92, 64
	s_addc_u32 s93, s93, 0
	v_mfma_f32_16x16x32_bf16 v[38:41], v[130:133], v[138:141], v[38:41]
	v_mfma_f32_16x16x32_bf16 v[6:9], v[134:137], v[138:141], v[6:9]
	s_waitcnt lgkmcnt(0)
	s_barrier
	v_mfma_f32_16x16x32_bf16 v[154:157], v[122:125], v[162:165], v[154:157]
	s_add_i32 s28, s31, 0xffff0000
	s_and_b32 s35, s28, 0x18000
	v_add_u32_e32 v187, s35, v200
	v_add_u32_e32 v226, s35, v201
	ds_read_b128 v[150:153], v226
	v_mfma_f32_16x16x32_bf16 v[90:93], v[126:129], v[162:165], v[90:93]
	ds_read_b128 v[146:149], v226 offset:1024
	v_mfma_f32_16x16x32_bf16 v[58:61], v[130:133], v[162:165], v[58:61]
	ds_read_b128 v[142:145], v226 offset:2048
	v_mfma_f32_16x16x32_bf16 v[26:29], v[134:137], v[162:165], v[26:29]
	ds_read_b128 v[138:141], v226 offset:3072
	v_mfma_f32_16x16x32_bf16 v[114:117], v[122:125], v[166:169], v[114:117]
	ds_read_b128 v[174:177], v187
	v_mfma_f32_16x16x32_bf16 v[82:85], v[126:129], v[166:169], v[82:85]
	ds_read_b128 v[170:173], v187 offset:1024
	v_mfma_f32_16x16x32_bf16 v[50:53], v[130:133], v[166:169], v[50:53]
	ds_read_b128 v[162:165], v187 offset:3072
	v_mfma_f32_16x16x32_bf16 v[18:21], v[134:137], v[166:169], v[18:21]
	ds_read_b128 v[166:169], v187 offset:2048
	v_mfma_f32_16x16x32_bf16 v[106:109], v[122:125], v[232:235], v[106:109]
	v_mfma_f32_16x16x32_bf16 v[74:77], v[126:129], v[232:235], v[74:77]
	v_mfma_f32_16x16x32_bf16 v[42:45], v[130:133], v[232:235], v[42:45]
	v_mfma_f32_16x16x32_bf16 v[10:13], v[134:137], v[232:235], v[10:13]
	v_mfma_f32_16x16x32_bf16 v[98:101], v[122:125], v[236:239], v[98:101]
	v_mfma_f32_16x16x32_bf16 v[66:69], v[126:129], v[236:239], v[66:69]
	v_mfma_f32_16x16x32_bf16 v[34:37], v[130:133], v[236:239], v[34:37]
	v_mfma_f32_16x16x32_bf16 v[2:5], v[134:137], v[236:239], v[2:5]
	s_waitcnt vmcnt(4)
	s_waitcnt lgkmcnt(0)
	s_barrier
	v_mfma_f32_16x16x32_bf16 v[158:161], v[174:177], v[150:153], v[158:161]
	v_mfma_f32_16x16x32_bf16 v[94:97], v[170:173], v[150:153], v[94:97]
	v_add_u32_e32 v226, s35, v230
	ds_read_b128 v[232:235], v226
	v_mfma_f32_16x16x32_bf16 v[62:65], v[166:169], v[150:153], v[62:65]
	ds_read_b128 v[236:239], v226 offset:1024
	v_mfma_f32_16x16x32_bf16 v[30:33], v[162:165], v[150:153], v[30:33]
	ds_read_b128 v[182:185], v226 offset:2048
	v_mfma_f32_16x16x32_bf16 v[118:121], v[174:177], v[146:149], v[118:121]
	ds_read_b128 v[178:181], v226 offset:3072
	s_add_i32 s89, s34, s88
	s_mov_b32 m0, s89
	v_mfma_f32_16x16x32_bf16 v[86:89], v[170:173], v[146:149], v[86:89]
	v_mfma_f32_16x16x32_bf16 v[54:57], v[166:169], v[146:149], v[54:57]
	global_load_lds_dwordx4 v186, s[90:91]
	s_add_i32 m0, s89, 0x2000
	v_mfma_f32_16x16x32_bf16 v[22:25], v[162:165], v[146:149], v[22:25]
	v_mfma_f32_16x16x32_bf16 v[110:113], v[174:177], v[142:145], v[110:113]
	v_mfma_f32_16x16x32_bf16 v[78:81], v[170:173], v[142:145], v[78:81]
	global_load_lds_dwordx4 v188, s[90:91]
	s_add_i32 m0, s89, 0x4000
	v_mfma_f32_16x16x32_bf16 v[46:49], v[166:169], v[142:145], v[46:49]
	v_mfma_f32_16x16x32_bf16 v[14:17], v[162:165], v[142:145], v[14:17]
	global_load_lds_dwordx4 v190, s[92:93]
	s_add_i32 m0, s89, 0x6000
	v_mfma_f32_16x16x32_bf16 v[102:105], v[174:177], v[138:141], v[102:105]
	v_mfma_f32_16x16x32_bf16 v[70:73], v[170:173], v[138:141], v[70:73]
	global_load_lds_dwordx4 v192, s[92:93]
	s_add_u32 s90, s90, 64
	s_addc_u32 s91, s91, 0
	s_add_u32 s92, s92, 64
	s_addc_u32 s93, s93, 0
	v_mfma_f32_16x16x32_bf16 v[38:41], v[166:169], v[138:141], v[38:41]
	v_mfma_f32_16x16x32_bf16 v[6:9], v[162:165], v[138:141], v[6:9]
	s_waitcnt lgkmcnt(0)
	s_barrier
	v_mfma_f32_16x16x32_bf16 v[154:157], v[174:177], v[232:235], v[154:157]
	s_add_i32 s24, s31, 0xffff8000
	s_and_b32 s24, s24, 0x10000
	v_add_u32_e32 v187, s24, v200
	v_add_u32_e32 v226, s24, v201
	ds_read_b128 v[150:153], v226
	v_mfma_f32_16x16x32_bf16 v[90:93], v[170:173], v[232:235], v[90:93]
	ds_read_b128 v[146:149], v226 offset:1024
	v_mfma_f32_16x16x32_bf16 v[58:61], v[166:169], v[232:235], v[58:61]
	ds_read_b128 v[142:145], v226 offset:2048
	v_mfma_f32_16x16x32_bf16 v[26:29], v[162:165], v[232:235], v[26:29]
	ds_read_b128 v[138:141], v226 offset:3072
	v_mfma_f32_16x16x32_bf16 v[114:117], v[174:177], v[236:239], v[114:117]
	ds_read_b128 v[122:125], v187
	v_mfma_f32_16x16x32_bf16 v[82:85], v[170:173], v[236:239], v[82:85]
	ds_read_b128 v[126:129], v187 offset:1024
	v_mfma_f32_16x16x32_bf16 v[50:53], v[166:169], v[236:239], v[50:53]
	ds_read_b128 v[130:133], v187 offset:2048
	v_mfma_f32_16x16x32_bf16 v[18:21], v[162:165], v[236:239], v[18:21]
	ds_read_b128 v[134:137], v187 offset:3072
	s_add_i32 s19, s19, 2
	s_add_u32 s20, s20, 0x80
	s_addc_u32 s21, s21, 0
	s_add_i32 s31, s31, 0x10000
	v_mfma_f32_16x16x32_bf16 v[106:109], v[174:177], v[182:185], v[106:109]
	v_mfma_f32_16x16x32_bf16 v[74:77], v[170:173], v[182:185], v[74:77]
	v_mfma_f32_16x16x32_bf16 v[42:45], v[166:169], v[182:185], v[42:45]
	v_mfma_f32_16x16x32_bf16 v[10:13], v[162:165], v[182:185], v[10:13]
	v_mfma_f32_16x16x32_bf16 v[98:101], v[174:177], v[178:181], v[98:101]
	v_mfma_f32_16x16x32_bf16 v[66:69], v[170:173], v[178:181], v[66:69]
	v_mfma_f32_16x16x32_bf16 v[34:37], v[166:169], v[178:181], v[34:37]
	v_mfma_f32_16x16x32_bf16 v[2:5], v[162:165], v[178:181], v[2:5]
	s_cmp_lt_u32 s19, 28
	s_cbranch_scc1 .Lgf_G4x_top
	s_branch .LBB0_183

.Lgf_G1x_top:
	s_waitcnt vmcnt(4)
	s_waitcnt lgkmcnt(0)
	s_barrier
	v_mfma_f32_16x16x32_bf16 v[126:129], v[130:133], v[158:161], v[126:129]
	v_mfma_f32_16x16x32_bf16 v[98:101], v[134:137], v[158:161], v[98:101]
	s_add_i32 s28, s31, 0xfffe8000
	s_and_b32 s34, s28, 0x10000
	v_add_u32_e32 v170, s34, v233
	ds_read_b128 v[162:165], v170
	v_mfma_f32_16x16x32_bf16 v[66:69], v[138:141], v[158:161], v[66:69]
	ds_read_b128 v[166:169], v170 offset:1024
	v_mfma_f32_16x16x32_bf16 v[34:37], v[142:145], v[158:161], v[34:37]
	ds_read_b128 v[234:237], v170 offset:2048
	v_mfma_f32_16x16x32_bf16 v[122:125], v[130:133], v[154:157], v[122:125]
	ds_read_b128 v[238:241], v170 offset:3072
	s_and_b32 s40, s31, 0x18000
	s_add_i32 s40, s40, s69
	s_mov_b32 m0, s40
	v_mfma_f32_16x16x32_bf16 v[90:93], v[134:137], v[154:157], v[90:93]
	v_mfma_f32_16x16x32_bf16 v[58:61], v[138:141], v[154:157], v[58:61]
	global_load_lds_dwordx4 v188, s[94:95]
	s_add_i32 m0, s40, 0x2000
	v_mfma_f32_16x16x32_bf16 v[26:29], v[142:145], v[154:157], v[26:29]
	v_mfma_f32_16x16x32_bf16 v[118:121], v[130:133], v[150:153], v[118:121]
	v_mfma_f32_16x16x32_bf16 v[86:89], v[134:137], v[150:153], v[86:89]
	global_load_lds_dwordx4 v190, s[94:95]
	s_add_i32 m0, s40, 0x4000
	v_mfma_f32_16x16x32_bf16 v[54:57], v[138:141], v[150:153], v[54:57]
	v_mfma_f32_16x16x32_bf16 v[22:25], v[142:145], v[150:153], v[22:25]
	global_load_lds_dwordx4 v192, s[42:43]
	s_add_i32 m0, s40, 0x6000
	v_mfma_f32_16x16x32_bf16 v[114:117], v[130:133], v[146:149], v[114:117]
	v_mfma_f32_16x16x32_bf16 v[82:85], v[134:137], v[146:149], v[82:85]
	global_load_lds_dwordx4 v194, s[42:43]
	s_add_u32 s94, s94, 64
	s_addc_u32 s95, s95, 0
	s_add_u32 s42, s42, 64
	s_addc_u32 s43, s43, 0
	v_mfma_f32_16x16x32_bf16 v[50:53], v[138:141], v[146:149], v[50:53]
	v_mfma_f32_16x16x32_bf16 v[18:21], v[142:145], v[146:149], v[18:21]
	s_waitcnt lgkmcnt(0)
	s_barrier
	v_mfma_f32_16x16x32_bf16 v[110:113], v[130:133], v[162:165], v[110:113]
	s_add_i32 s28, s31, 0xffff0000
	s_and_b32 s35, s28, 0x18000
	v_add_u32_e32 v189, s35, v231
	v_add_u32_e32 v226, s35, v232
	ds_read_b128 v[158:161], v226
	v_mfma_f32_16x16x32_bf16 v[78:81], v[134:137], v[162:165], v[78:81]
	ds_read_b128 v[154:157], v226 offset:1024
	v_mfma_f32_16x16x32_bf16 v[46:49], v[138:141], v[162:165], v[46:49]
	ds_read_b128 v[150:153], v226 offset:2048
	v_mfma_f32_16x16x32_bf16 v[14:17], v[142:145], v[162:165], v[14:17]
	ds_read_b128 v[146:149], v226 offset:3072
	v_mfma_f32_16x16x32_bf16 v[106:109], v[130:133], v[166:169], v[106:109]
	ds_read_b128 v[174:177], v189
	v_mfma_f32_16x16x32_bf16 v[74:77], v[134:137], v[166:169], v[74:77]
	ds_read_b128 v[170:173], v189 offset:1024
	v_mfma_f32_16x16x32_bf16 v[42:45], v[138:141], v[166:169], v[42:45]
	ds_read_b128 v[162:165], v189 offset:3072
	v_mfma_f32_16x16x32_bf16 v[10:13], v[142:145], v[166:169], v[10:13]
	ds_read_b128 v[166:169], v189 offset:2048
	v_mfma_f32_16x16x32_bf16 v[102:105], v[130:133], v[234:237], v[102:105]
	v_mfma_f32_16x16x32_bf16 v[70:73], v[134:137], v[234:237], v[70:73]
	v_mfma_f32_16x16x32_bf16 v[38:41], v[138:141], v[234:237], v[38:41]
	v_mfma_f32_16x16x32_bf16 v[6:9], v[142:145], v[234:237], v[6:9]
	v_mfma_f32_16x16x32_bf16 v[94:97], v[130:133], v[238:241], v[94:97]
	v_mfma_f32_16x16x32_bf16 v[62:65], v[134:137], v[238:241], v[62:65]
	v_mfma_f32_16x16x32_bf16 v[30:33], v[138:141], v[238:241], v[30:33]
	v_mfma_f32_16x16x32_bf16 v[2:5], v[142:145], v[238:241], v[2:5]
	s_waitcnt vmcnt(4)
	s_waitcnt lgkmcnt(0)
	s_barrier
	v_mfma_f32_16x16x32_bf16 v[126:129], v[174:177], v[158:161], v[126:129]
	v_mfma_f32_16x16x32_bf16 v[98:101], v[170:173], v[158:161], v[98:101]
	v_add_u32_e32 v226, s35, v233
	ds_read_b128 v[234:237], v226
	v_mfma_f32_16x16x32_bf16 v[66:69], v[166:169], v[158:161], v[66:69]
	ds_read_b128 v[238:241], v226 offset:1024
	v_mfma_f32_16x16x32_bf16 v[34:37], v[162:165], v[158:161], v[34:37]
	ds_read_b128 v[182:185], v226 offset:2048
	v_mfma_f32_16x16x32_bf16 v[122:125], v[174:177], v[154:157], v[122:125]
	ds_read_b128 v[178:181], v226 offset:3072
	s_add_i32 s40, s34, s69
	s_mov_b32 m0, s40
	v_mfma_f32_16x16x32_bf16 v[90:93], v[170:173], v[154:157], v[90:93]
	v_mfma_f32_16x16x32_bf16 v[58:61], v[166:169], v[154:157], v[58:61]
	global_load_lds_dwordx4 v188, s[94:95]
	s_add_i32 m0, s40, 0x2000
	v_mfma_f32_16x16x32_bf16 v[26:29], v[162:165], v[154:157], v[26:29]
	v_mfma_f32_16x16x32_bf16 v[118:121], v[174:177], v[150:153], v[118:121]
	v_mfma_f32_16x16x32_bf16 v[86:89], v[170:173], v[150:153], v[86:89]
	global_load_lds_dwordx4 v190, s[94:95]
	s_add_i32 m0, s40, 0x4000
	v_mfma_f32_16x16x32_bf16 v[54:57], v[166:169], v[150:153], v[54:57]
	v_mfma_f32_16x16x32_bf16 v[22:25], v[162:165], v[150:153], v[22:25]
	global_load_lds_dwordx4 v192, s[42:43]
	s_add_i32 m0, s40, 0x6000
	v_mfma_f32_16x16x32_bf16 v[114:117], v[174:177], v[146:149], v[114:117]
	v_mfma_f32_16x16x32_bf16 v[82:85], v[170:173], v[146:149], v[82:85]
	global_load_lds_dwordx4 v194, s[42:43]
	s_add_u32 s94, s94, 64
	s_addc_u32 s95, s95, 0
	s_add_u32 s42, s42, 64
	s_addc_u32 s43, s43, 0
	v_mfma_f32_16x16x32_bf16 v[50:53], v[166:169], v[146:149], v[50:53]
	v_mfma_f32_16x16x32_bf16 v[18:21], v[162:165], v[146:149], v[18:21]
	s_waitcnt lgkmcnt(0)
	s_barrier
	v_mfma_f32_16x16x32_bf16 v[110:113], v[174:177], v[234:237], v[110:113]
	s_add_i32 s24, s31, 0xffff8000
	s_and_b32 s24, s24, 0x10000
	v_add_u32_e32 v189, s24, v231
	v_add_u32_e32 v226, s24, v232
	ds_read_b128 v[158:161], v226
	v_mfma_f32_16x16x32_bf16 v[78:81], v[170:173], v[234:237], v[78:81]
	ds_read_b128 v[154:157], v226 offset:1024
	v_mfma_f32_16x16x32_bf16 v[46:49], v[166:169], v[234:237], v[46:49]
	ds_read_b128 v[150:153], v226 offset:2048
	v_mfma_f32_16x16x32_bf16 v[14:17], v[162:165], v[234:237], v[14:17]
	ds_read_b128 v[146:149], v226 offset:3072
	v_mfma_f32_16x16x32_bf16 v[106:109], v[174:177], v[238:241], v[106:109]
	ds_read_b128 v[130:133], v189
	v_mfma_f32_16x16x32_bf16 v[74:77], v[170:173], v[238:241], v[74:77]
	ds_read_b128 v[134:137], v189 offset:1024
	v_mfma_f32_16x16x32_bf16 v[42:45], v[166:169], v[238:241], v[42:45]
	ds_read_b128 v[138:141], v189 offset:2048
	v_mfma_f32_16x16x32_bf16 v[10:13], v[162:165], v[238:241], v[10:13]
	ds_read_b128 v[142:145], v189 offset:3072
	s_add_i32 s30, s30, 2
	s_add_u32 s20, s20, 0x80
	s_addc_u32 s21, s21, 0
	s_add_i32 s31, s31, 0x10000
	v_mfma_f32_16x16x32_bf16 v[102:105], v[174:177], v[182:185], v[102:105]
	v_mfma_f32_16x16x32_bf16 v[70:73], v[170:173], v[182:185], v[70:73]
	v_mfma_f32_16x16x32_bf16 v[38:41], v[166:169], v[182:185], v[38:41]
	v_mfma_f32_16x16x32_bf16 v[6:9], v[162:165], v[182:185], v[6:9]
	v_mfma_f32_16x16x32_bf16 v[94:97], v[174:177], v[178:181], v[94:97]
	v_mfma_f32_16x16x32_bf16 v[62:65], v[170:173], v[178:181], v[62:65]
	v_mfma_f32_16x16x32_bf16 v[30:33], v[166:169], v[178:181], v[30:33]
	v_mfma_f32_16x16x32_bf16 v[2:5], v[162:165], v[178:181], v[2:5]
	s_cmp_lt_u32 s30, 28
	s_cbranch_scc1 .Lgf_G1x_top
	s_branch .LBB0_645
